# scan: start stepping as soon as the first chunk's operands have landed (prologue waits vmcnt(18) instead of vmcnt(0); the in-loop counted waits cover the later chunks)
# baseline (speedup 1.0000x reference)
.LBB0_652:
	s_andn2_b64 vcc, exec, s[0:1]
	s_cbranch_vccnz .LBB0_704
	v_and_b32_e32 v14, 63, v206
	v_lshrrev_b32_e32 v15, 6, v206
	v_and_b32_e32 v64, 15, v14
	v_readfirstlane_b32 s11, v15
	v_lshrrev_b32_e32 v65, 4, v14
	v_lshlrev_b32_e32 v66, 2, v206
	ds_write_b32 v66, v0
	ds_write_b32 v66, v0 offset:2048
	ds_write_b32 v66, v0 offset:4096
	ds_write_b32 v66, v0 offset:6144
	ds_write_b32 v66, v0 offset:8192
	s_and_b32 s12, s11, 3
	s_and_b32 s13, s72, 7
	s_lshr_b32 s14, s72, 5
	s_bfe_u32 s15, s72, 0x20003
	s_lshl_b32 s16, s14, 3
	s_add_u32 s16, s16, s13
	s_lshl_b32 s17, s16, 21
	s_mov_b32 s18, 0x13800000
	s_cmp_lt_u32 s11, 4
	s_cselect_b32 s18, 0x11800000, s18
	s_add_u32 s18, s18, s17
	s_lshl_b32 s19, s12, 12
	s_add_u32 s18, s18, s19
	s_add_u32 s0, s70, s18
	s_addc_u32 s1, s71, 0
	s_lshl_b32 s19, s11, 11
	s_add_u32 s18, s17, s19
	s_add_u32 s18, s18, 0x15800000
	s_add_u32 s4, s70, s18
	s_addc_u32 s5, s71, 0
	s_lshl_b32 s18, s16, 9
	s_add_u32 s18, s18, 0x11500000
	s_add_u32 s6, s70, s18
	s_addc_u32 s7, s71, 0
	s_lshl_b32 s18, s15, 12
	s_lshl_b32 s19, s12, 9
	s_add_u32 s18, s18, s19
	s_add_u32 s18, s18, s17
	s_add_u32 s18, s18, 0x17800000
	s_lshl_b32 s19, s16, 20
	s_lshl_b32 s20, s12, 11
	s_add_u32 s19, s19, s20
	s_add_u32 s19, s19, 0x19800000
	s_cmp_lt_u32 s11, 4
	s_cselect_b32 s18, s18, s19
	s_add_u32 s2, s70, s18
	s_addc_u32 s3, s71, 0
	s_lshl_b32 s18, s14, 24
	s_lshl_b32 s19, s12, 15
	s_add_u32 s18, s18, s19
	s_lshl_b32 s19, s13, 8
	s_add_u32 s18, s18, s19
	s_lshl_b32 s19, s15, 6
	s_add_u32 s18, s18, s19
	s_add_u32 s18, s18, 0xb400000
	s_add_u32 s8, s70, s18
	s_addc_u32 s9, s71, 0
	v_lshlrev_b32_e32 v1, 4, v14
	v_mov_b32_e32 v3, 0
	v_mul_u32_u24_e32 v8, 0x110, v64
	v_mul_u32_u24_e32 v9, 0x90, v64
	v_lshl_add_u32 v11, v65, 3, v8
	v_lshl_add_u32 v10, v65, 3, v9
	v_lshl_add_u32 v8, v65, 4, v8
	v_lshl_add_u32 v9, v65, 4, v9
	s_lshl_b32 s18, s11, 5
	v_add_u32_e32 v11, s18, v11
	s_lshl_b32 s18, s12, 5
	v_add_u32_e32 v10, s18, v10
	s_mul_i32 s18, s12, 0x500
	s_add_u32 s18, s18, 0x5800
	v_mul_u32_u24_e32 v13, 0x140, v65
	v_lshl_add_u32 v13, v64, 1, v13
	v_add_u32_e32 v13, s18, v13
	v_lshrrev_b32_e32 v67, 2, v14
	v_and_b32_e32 v68, 3, v14
	v_mul_u32_u24_e32 v172, 0x50, v67
	v_lshl_add_u32 v172, v68, 4, v172
	v_add_u32_e32 v172, s18, v172
	v_lshlrev_b32_e32 v12, 11, v67
	v_lshl_add_u32 v12, v68, 4, v12
	v_mov_b32_e32 v16, 0
	v_mov_b32_e32 v17, 0
	v_mov_b32_e32 v18, 0
	v_mov_b32_e32 v19, 0
	v_mov_b32_e32 v20, 0
	v_mov_b32_e32 v21, 0
	v_mov_b32_e32 v22, 0
	v_mov_b32_e32 v23, 0
	s_cmp_lt_u32 s11, 4
	s_waitcnt lgkmcnt(0)
	s_barrier
	s_cbranch_scc0 .Lscan_O_path
	v_lshlrev_b32_e32 v2, 3, v14
	global_load_dwordx4 v[72:75], v1, s[0:1]
	global_load_dwordx4 v[76:79], v1, s[0:1] offset:1024
	global_load_dwordx4 v[80:83], v1, s[0:1] offset:2048
	global_load_dwordx4 v[84:87], v1, s[0:1] offset:3072
	global_load_dwordx2 v[88:89], v2, s[2:3]
	global_load_dwordx2 v[90:91], v2, s[2:3] offset:2048
	global_load_dwordx4 v[96:99], v1, s[4:5]
	global_load_dwordx4 v[100:103], v1, s[4:5] offset:1024
	global_load_dword v184, v3, s[6:7]
	v_add_u32_e32 v1, 0x4000, v1
	v_add_u32_e32 v2, 0x4000, v2
	v_add_u32_e32 v3, 4, v3
	global_load_dwordx4 v[104:107], v1, s[0:1]
	global_load_dwordx4 v[108:111], v1, s[0:1] offset:1024
	global_load_dwordx4 v[112:115], v1, s[0:1] offset:2048
	global_load_dwordx4 v[116:119], v1, s[0:1] offset:3072
	global_load_dwordx2 v[120:121], v2, s[2:3]
	global_load_dwordx2 v[122:123], v2, s[2:3] offset:2048
	global_load_dwordx4 v[128:131], v1, s[4:5]
	global_load_dwordx4 v[132:135], v1, s[4:5] offset:1024
	global_load_dword v185, v3, s[6:7]
	v_add_u32_e32 v1, 0x4000, v1
	v_add_u32_e32 v2, 0x4000, v2
	v_add_u32_e32 v3, 4, v3
	global_load_dwordx4 v[136:139], v1, s[0:1]
	global_load_dwordx4 v[140:143], v1, s[0:1] offset:1024
	global_load_dwordx4 v[144:147], v1, s[0:1] offset:2048
	global_load_dwordx4 v[148:151], v1, s[0:1] offset:3072
	global_load_dwordx2 v[188:189], v2, s[2:3]
	global_load_dwordx2 v[190:191], v2, s[2:3] offset:2048
	global_load_dwordx4 v[196:199], v1, s[4:5]
	global_load_dwordx4 v[200:203], v1, s[4:5] offset:1024
	global_load_dword v186, v3, s[6:7]
	v_add_u32_e32 v1, 0x4000, v1
	v_add_u32_e32 v2, 0x4000, v2
	v_add_u32_e32 v3, 4, v3
	s_waitcnt vmcnt(18)
	s_movk_i32 s10, 32

.Lscan_O_path:
	v_lshlrev_b32_e32 v2, 4, v14
	global_load_dwordx4 v[72:75], v1, s[0:1]
	global_load_dwordx4 v[76:79], v1, s[0:1] offset:1024
	global_load_dwordx4 v[80:83], v1, s[0:1] offset:2048
	global_load_dwordx4 v[84:87], v1, s[0:1] offset:3072
	global_load_dwordx4 v[88:91], v2, s[2:3]
	global_load_dwordx4 v[92:95], v2, s[2:3] offset:1024
	global_load_dwordx4 v[96:99], v1, s[4:5]
	global_load_dwordx4 v[100:103], v1, s[4:5] offset:1024
	global_load_dword v184, v3, s[6:7]
	v_add_u32_e32 v1, 0x4000, v1
	v_add_u32_e32 v2, 0x2000, v2
	v_add_u32_e32 v3, 4, v3
	global_load_dwordx4 v[104:107], v1, s[0:1]
	global_load_dwordx4 v[108:111], v1, s[0:1] offset:1024
	global_load_dwordx4 v[112:115], v1, s[0:1] offset:2048
	global_load_dwordx4 v[116:119], v1, s[0:1] offset:3072
	global_load_dwordx4 v[120:123], v2, s[2:3]
	global_load_dwordx4 v[124:127], v2, s[2:3] offset:1024
	global_load_dwordx4 v[128:131], v1, s[4:5]
	global_load_dwordx4 v[132:135], v1, s[4:5] offset:1024
	global_load_dword v185, v3, s[6:7]
	v_add_u32_e32 v1, 0x4000, v1
	v_add_u32_e32 v2, 0x2000, v2
	v_add_u32_e32 v3, 4, v3
	global_load_dwordx4 v[136:139], v1, s[0:1]
	global_load_dwordx4 v[140:143], v1, s[0:1] offset:1024
	global_load_dwordx4 v[144:147], v1, s[0:1] offset:2048
	global_load_dwordx4 v[148:151], v1, s[0:1] offset:3072
	global_load_dwordx4 v[188:191], v2, s[2:3]
	global_load_dwordx4 v[192:195], v2, s[2:3] offset:1024
	global_load_dwordx4 v[196:199], v1, s[4:5]
	global_load_dwordx4 v[200:203], v1, s[4:5] offset:1024
	global_load_dword v186, v3, s[6:7]
	v_add_u32_e32 v1, 0x4000, v1
	v_add_u32_e32 v2, 0x2000, v2
	v_add_u32_e32 v3, 4, v3
	s_waitcnt vmcnt(18)
	s_movk_i32 s10, 32
